# static priority raise scoped to the attention phase only: s_setprio 1 for waves 4-7 before the attention unit loop, s_setprio 0 after it
# speedup vs baseline: 1.0094x; 1.0087x over previous
; #define LAS __attribute__((address_space(3)))
; __device__ __forceinline__ void attn_unit(Frame& F, int b, int g, int sb) {
;     int tid = F.tid; asm volatile("" : "+v"(tid));
;     const int lane = tid & 63, wid = F.wave, r32 = lane & 31, hi = lane >> 5, hl = wid >> 1, rh = wid & 1;
;     const int sr = tid >> 4, sc = (tid & 15) * 8;
;     unsigned char* ws = F.ws; LAS unsigned char* lds = F.lds;
;     LAS float* wsf = (LAS float*)(lds + AT_WS) + wid * 64;
;     LAS float* lutw = (LAS float*)(lds + AT_LUT);
;     LAS float* gl = (LAS float*)(lds + AT_GL);
;     LAS unsigned* selm = (LAS unsigned*)(lds + AT_SEL);
;     LAS float* impS = (LAS float*)(lds + AT_IMPS);
;     LAS float* impH = (LAS float*)(lds + AT_IMPH);
;     const int h = g * 4 + hl, bg = b * NG + g, row = 32 * rh + r32, pos = 64 * sb + row;
;     const size_t kvs = KV_STRIDE_B / 2;
;     const bf16_t* kvb = (const bf16_t*)(ws + WS_KV);
;     const bf16_t* Ksel = kvb + 2 * kvs + (size_t)bg * SEQ * HD; const bf16_t* Vsel = kvb + 3 * kvs + (size_t)bg * SEQ * HD;
;     const bf16_t* Kwin = kvb + 4 * kvs + (size_t)bg * SEQ * HD; const bf16_t* Vwin = kvb + 5 * kvs + (size_t)bg * SEQ * HD;
;     const bf16_t* Kc = (const bf16_t*)(ws + WS_KCMP) + (size_t)bg * 128 * HD; const bf16_t* Vc = (const bf16_t*)(ws + WS_VCMP) + (size_t)bg * 128 * HD;
; __global__ void __launch_bounds__(512, 2) mk_fwd(Args args) {
;     ...
;         for (int u = blockIdx.x; u < 256; u += F.G) {
;             const int x = u & 7, k = u >> 3, bg = 2 * x + (k & 1), pr = k >> 1;
;             attn_unit(F, bg >> 2, bg & 3, 31 - pr);
.LBB0_2691:
	s_lshl_b32 s0, s49, 8
	v_readlane_b32 s2, v246, 7
	s_add_i32 s65, s0, 0
	s_lshl_b32 s0, s49, 5
	s_lshr_b32 s1, s2, 7
	s_add_i32 s96, s65, 0x14000
	s_and_b32 s59, s0, 32
	s_add_u32 s0, s50, 0x3a360000
	v_writelane_b32 v246, s0, 24
	s_addc_u32 s0, s51, 0
	v_writelane_b32 v246, s0, 25
	s_add_u32 s0, s50, 0x3a460000
	v_writelane_b32 v246, s0, 26
	s_addc_u32 s0, s51, 0
	s_add_u32 s4, s50, 0x3a560000
	v_writelane_b32 v246, s0, 27
	s_addc_u32 s5, s51, 0
	v_writelane_b32 v246, s4, 28
	s_add_u32 s0, s50, 0x35300000
	s_waitcnt vmcnt(0)
	v_mbcnt_lo_u32_b32 v1, -1, 0
	v_writelane_b32 v246, s5, 29
	v_writelane_b32 v246, s0, 30
	s_addc_u32 s0, s51, 0
	v_writelane_b32 v246, s0, 31
	s_mul_i32 s0, s1, 0x4c0
	s_add_i32 s0, s0, 0
	s_add_i32 s97, s0, 0x14800
	s_lshl_b32 s82, s1, 6
	s_add_u32 s3, s50, 0x39b50000
	v_writelane_b32 v246, s3, 32
	s_addc_u32 s3, s51, 0
	v_writelane_b32 v246, s3, 33
	s_add_u32 s3, s50, 0x39340000
	v_writelane_b32 v246, s3, 34
	s_addc_u32 s3, s51, 0
	v_writelane_b32 v246, s3, 35
	s_add_u32 s3, s50, 0x38b30000
	v_writelane_b32 v246, s3, 36
	s_addc_u32 s3, s51, 0
	v_writelane_b32 v246, s3, 37
	s_add_u32 s3, s50, 0x38320000
	v_writelane_b32 v246, s3, 38
	s_addc_u32 s3, s51, 0
	v_writelane_b32 v246, s3, 39
	v_writelane_b32 v246, s1, 40
	s_lshl_b32 s1, s1, 8
	s_add_i32 s1, s1, 0
	s_add_i32 s64, s1, 0x15b00
	s_lshl_b32 s1, s2, 1
	s_and_b32 s1, s1, 0x80
	s_add_i32 s1, s0, s1
	s_add_i32 s2, s1, 0x16794
	v_writelane_b32 v246, s2, 41
	s_add_i32 s2, s1, 0x16f94
	v_writelane_b32 v246, s2, 42
	s_add_i32 s0, s0, 0x14894
	v_writelane_b32 v246, s0, 43
	s_add_i32 s0, s1, 0x15094
	v_writelane_b32 v246, s0, 44
	s_add_i32 s0, 0, 0x27c80
	v_writelane_b32 v246, s0, 45
	s_add_i32 s0, 0, 0x14800
	v_writelane_b32 v246, s0, 46
	s_add_i32 s0, 0, 0x16300
	v_writelane_b32 v246, s0, 47
	s_add_i32 s0, 0, 0xc000
	v_writelane_b32 v246, s0, 21
	s_add_i32 s26, 0, 0x18900
	s_mov_b32 s58, 0x14000
	s_movk_i32 s63, 0x4c0
	s_xor_b32 s95, s59, 0xb0
	s_mov_b32 s70, 0x6bca1af3
	s_movk_i32 s94, 0x60
	s_movk_i32 s65, 0x42
	s_movk_i32 s76, 0x4c
	s_movk_i32 s18, 0x56
	s_movk_i32 s19, 0x62
	s_movk_i32 s69, 0x70
	s_movk_i32 s80, 0x2bf
	v_mov_b32_e32 v3, 0
	s_movk_i32 s21, 0x4000
	s_movk_i32 s22, 0xff
	s_mov_b32 s23, 0x10000
	s_movk_i32 s24, 0x84
	s_movk_i32 s25, 0x2000
	s_movk_i32 s27, 0x6000
	s_mov_b32 s28, 0x12000
	s_mov_b32 s29, 0x16000
	s_mov_b32 s30, 0x20000
	v_mbcnt_hi_u32_b32 v1, -1, v1
	v_mov_b32_e32 v162, 0xdf
	v_mov_b32_e32 v163, 0xff800000
	s_mov_b32 s31, 0x22000
	s_mov_b32 s34, 0x24000
	s_mov_b32 s35, 0x26000
	s_mov_b32 s36, 0x30000
	s_mov_b32 s37, 0x32000
	s_mov_b32 s50, 0x34000
	s_mov_b32 s51, 0x36000
	s_add_i32 s47, 0, 0x16800
	s_brev_b32 s33, -3
	s_mov_b32 s81, 0x40c00000
	s_movk_i32 s68, 0xfdff
	s_mov_b32 s79, 0
	v_writelane_b32 v246, s26, 48
	s_barrier
	v_writelane_b32 v246, s47, 49
	v_readfirstlane_b32 s98, v0
	s_nop 3
	s_lshr_b32 s98, s98, 6
	s_cmp_lt_u32 s98, 4
	s_cbranch_scc1 .Lmy_ap_skip
	s_setprio 1
.Lmy_ap_skip:
	s_branch .LBB0_2693
.LBB0_2692:
	s_or_b64 exec, exec, s[0:1]
	s_add_i32 s74, s74, s71
	s_cmpk_gt_i32 s74, 0xff
	s_cbranch_scc1 .LBB0_3670

; #define GRID_BAR() do { if (N_LAUNCHES != PER_PHASE) xcd_barrier(bar); } while (0)
; __device__ __forceinline__ void xcd_barrier(const XcdBarrier& b) {
;     asm volatile("s_waitcnt vmcnt(0)" ::: "memory");
;     __syncthreads();
;     if (threadIdx.x == 0) {
;         unsigned* bar = b.bar;
;         __builtin_amdgcn_s_waitcnt(0);
;         unsigned nloc = b.st[0], nx = b.st[1];
;         if (nloc == 0u) { xcd_barrier_complete(bar, b.x, nloc, nx); b.st[0] = nloc; b.st[1] = nx; }
; __global__ void __launch_bounds__(512, 2) mk_fwd(Args args) {
;     ...
;     if (IN(6)) {
;         pg8::Gemm g{ws + WS_YMIX, ws + WS_WOUT, DM, 2}; pg8::StaticOrder S; S.init(M, DM, F.G, (int)blockIdx.x);
;         EpiResid E{nullptr, F.out, nullptr, nullptr, 1.0f, actb};
;         pg8::gemm_phase(F.lds, g, S, E);
;         GRID_BAR();
.LBB0_3670:
	s_setprio 0
	v_readlane_b32 s4, v246, 10
	v_readlane_b32 s5, v246, 11
	v_readlane_b32 s76, v246, 13
	s_cmp_gt_i32 s5, 6
	v_readlane_b32 s77, v246, 14
	v_readlane_b32 s78, v246, 15
	v_readlane_b32 s79, v246, 16
	v_readlane_b32 s68, v246, 17
	v_readlane_b32 s69, v246, 18
	s_cbranch_scc0 .LBB0_3724
	s_waitcnt vmcnt(0)
	s_waitcnt lgkmcnt(0)
	s_barrier
	s_mov_b64 s[0:1], exec
	v_readlane_b32 s2, v246, 3
	v_readlane_b32 s3, v246, 4
	s_and_b64 s[2:3], s[0:1], s[2:3]
	s_mov_b64 exec, s[2:3]
	s_cbranch_execz .LBB0_3723
	s_add_i32 s2, 0, 0x27960
	v_mov_b32_e32 v1, s2
	s_waitcnt vmcnt(0) expcnt(0) lgkmcnt(0)
	ds_read_b32 v3, v1
	s_add_i32 s2, 0, 0x27964
	v_mov_b32_e32 v1, s2
	ds_read_b32 v1, v1
	s_waitcnt lgkmcnt(1)
	v_cmp_ne_u32_e32 vcc, 0, v3
	s_cbranch_vccnz .LBB0_3687
	v_readlane_b32 s2, v246, 0
	v_readlane_b32 s3, v246, 1
	s_load_dwordx2 s[6:7], s[2:3], 0x4
	s_add_u32 s2, s60, 0x1000
	s_addc_u32 s3, s61, 0
	s_add_u32 s4, s60, 0x1100
	s_addc_u32 s5, s61, 0
	s_waitcnt lgkmcnt(0)
	s_mul_i32 s16, s6, s71
	s_add_u32 s6, s60, 0x1200
	s_mul_i32 s16, s16, s7
	s_addc_u32 s7, s61, 0
	s_add_u32 s8, s60, 0x1300
	s_addc_u32 s9, s61, 0
	s_mov_b32 s17, 1
	v_mov_b32_e32 v17, 0
	s_branch .LBB0_3675
